# speedup vs baseline: 1.0035x; 1.0014x over previous
; __global__ void __launch_bounds__(512, 2) fwd_megakernel(Params p) {
;     ...
;   if (blockIdx.x == 0) for (int i = tid_raw(); i < XCD_BAR_WORDS; i += NT) bar[i] = 0u;
;   grid.sync();
.LBB0_14:
	v_lshrrev_b32_e32 v2, 20, v0
	v_lshrrev_b32_e32 v0, 10, v0
	v_or_b32_e32 v0, v0, v2
	s_movk_i32 s4, 0x3ff
	v_and_or_b32 v0, v0, s4, v6
	v_cmp_eq_u32_e32 vcc, 0, v0
	s_barrier
	s_and_saveexec_b64 s[4:5], vcc
	s_cbranch_execz .LBB0_24
	v_readlane_b32 s6, v252, 0
	v_readlane_b32 s7, v252, 1
	s_cmp_lg_u32 s74, 0
	s_cbranch_scc1 .Lmy_cg_skipwb
	buffer_wbl2 sc1
.Lmy_cg_skipwb:
	s_waitcnt vmcnt(0)
	s_load_dwordx2 s[6:7], s[6:7], 0x58
	v_mov_b32_e32 v3, 0
	s_mov_b64 s[8:9], exec
	v_mbcnt_lo_u32_b32 v2, s8, 0
	v_mbcnt_hi_u32_b32 v2, s9, v2
	s_waitcnt lgkmcnt(0)
	global_load_dword v0, v3, s[6:7] offset:40
	v_cmp_eq_u32_e32 vcc, 0, v2
	s_and_saveexec_b64 s[10:11], vcc
	s_cbranch_execz .LBB0_17
	s_bcnt1_i32_b64 s8, s[8:9]
	v_mov_b32_e32 v4, s8
	global_atomic_add v4, v3, v4, s[6:7] offset:32 sc0
